# a23 + ret_scan (G==256 path): each thread scans 2 adjacent bf16 elements with dword loads/stores, 32 loads in flight, single pass; XCD owns heads 2x,2x+1
# baseline (speedup 1.0000x reference)
.LBB0_805:
	s_or_b64 exec, exec, s[0:1]
	s_add_u32 s18, s26, 0xa900000
	s_addc_u32 s19, s27, 0
	s_and_b32 s64, s2, 7
	s_lshl_b32 s64, s64, 5
	s_lshr_b32 s67, s2, 3
	s_or_b32 s64, s64, s67
	s_lshl_b32 s64, s64, 9
	s_cmp_eq_u32 s28, 0x100
	s_cselect_b32 s64, s64, s3
	s_add_i32 s0, s33, s64
	s_waitcnt lgkmcnt(0)
	s_barrier
	v_mbcnt_lo_u32_b32 v0, -1, 0
	v_mbcnt_hi_u32_b32 v0, -1, v0
	s_nop 0
	v_add_u32_e32 v4, s0, v0
	s_mov_b32 s71, s34
	s_cmp_eq_u32 s28, 0x100
	s_cbranch_scc0 .Lmy_rs_old1
	s_mov_b32 s71, 0x40000
	v_add_u32_e32 v11, s33, v0
	s_lshr_b32 s69, s2, 3
	s_lshl_b32 s69, s69, 9
	v_add_u32_e32 v12, s69, v11
	v_and_b32_e32 v13, 0xfff, v12
	v_lshlrev_b32_e32 v13, 1, v13
	v_lshrrev_b32_e32 v12, 12, v12
	v_lshrrev_b32_e32 v14, 1, v12
	v_lshlrev_b32_e32 v14, 17, v14
	v_and_b32_e32 v12, 1, v12
	s_and_b32 s70, s2, 7
	s_lshl_b32 s70, s70, 1
	v_add_u32_e32 v12, s70, v12
	v_lshlrev_b32_e32 v12, 13, v12
	v_or3_b32 v4, v14, v12, v13
	v_mov_b32_e32 v14, 0x40000
	v_cmp_gt_u32_e32 vcc, 0x200, v11
	s_nop 1
	v_cndmask_b32_e32 v4, v14, v4, vcc
.Lmy_rs_old1:
	s_mov_b32 s0, 0x40000
	v_cmp_gt_i32_e32 vcc, s0, v4
	s_and_saveexec_b64 s[16:17], vcc
	s_cbranch_execz .LBB0_810
	s_mov_b64 s[20:21], 0
	s_mov_b32 s3, 0x20000
	v_mov_b32_e32 v5, s53
	v_mov_b32_e32 v6, s51
	v_mov_b32_e32 v7, s52
	v_mov_b32_e32 v8, s50
	v_mov_b32_e32 v1, 0
	s_mov_b32 s8, 0x3fb8aa3b
	s_mov_b32 s9, 0xc2ce8ed0
	s_mov_b32 s22, 0x42b17218
	v_mov_b32_e32 v9, 0x7f800000
	s_mov_b32 s23, 0x3fffff0
	s_mov_b32 s35, 0x3ffff
.LBB0_807:
	v_cmp_gt_u32_e32 vcc, s3, v4
	v_lshrrev_b32_e32 v0, 11, v4
	v_and_b32_e32 v0, 28, v0
	v_cndmask_b32_e32 v3, v5, v6, vcc
	v_cndmask_b32_e32 v2, v7, v8, vcc
	v_lshl_add_u64 v[2:3], v[2:3], 0, v[0:1]
	global_load_dword v10, v[2:3], off
	v_bfe_u32 v0, v4, 13, 4
	v_ashrrev_i32_e32 v2, 13, v4
	v_and_b32_e32 v3, 0x1fff, v4
	v_and_or_b32 v0, v2, s23, v0
	v_lshlrev_b32_e32 v2, 6, v0
	v_lshlrev_b32_e32 v0, 1, v3
	s_waitcnt vmcnt(0)
	v_mul_f32_e32 v3, 0x3fb8aa3b, v10
	v_fma_f32 v11, v10, s8, -v3
	v_rndne_f32_e32 v12, v3
	v_fmac_f32_e32 v11, 0x32a5705f, v10
	v_sub_f32_e32 v3, v3, v12
	v_add_f32_e32 v3, v3, v11
	v_cvt_i32_f32_e32 v12, v12
	v_exp_f32_e32 v11, v3
	v_cmp_ngt_f32_e64 s[0:1], s9, v10
	v_ashrrev_i32_e32 v3, 31, v2
	v_lshlrev_b64 v[2:3], 14, v[2:3]
	v_ldexp_f32 v11, v11, v12
	v_cndmask_b32_e64 v11, 0, v11, s[0:1]
	v_cmp_nlt_f32_e64 s[0:1], s22, v10
	v_lshl_add_u64 v[2:3], s[18:19], 0, v[2:3]
	v_lshl_add_u64 v[2:3], v[2:3], 0, v[0:1]
	v_cndmask_b32_e64 v10, v9, v11, s[0:1]
	v_mul_f32_e32 v10, 0xbfb8aa3b, v10
	v_mul_f32_e32 v10, 0x43000000, v10
	v_exp_f32_e32 v10, v10
	s_cmp_eq_u32 s28, 0x100
	s_cbranch_scc1 .Lmy_rs_new
	s_mov_b32 s0, 56
	s_mov_b32 s1, 7
	v_mov_b32_e32 v0, 0
.LBB0_808:
	s_add_i32 s38, s1, -7
	s_add_i32 s39, s0, 7
	s_add_i32 s40, s1, -6
	s_add_i32 s41, s0, 6
	s_add_i32 s42, s1, -5
	s_add_i32 s43, s0, 5
	s_add_i32 s44, s1, -4
	s_add_i32 s45, s0, 4
	s_add_i32 s46, s1, -3
	s_add_i32 s47, s0, 3
	s_add_i32 s48, s1, -2
	s_add_i32 s49, s0, 2
	s_add_i32 s54, s1, -1
	s_add_i32 s55, s0, 1
	v_mov_b32_e32 v13, s39
	v_mov_b32_e32 v14, s38
	v_mov_b32_e32 v11, s0
	v_mov_b32_e32 v12, s1
	v_mov_b32_e32 v15, s41
	v_mov_b32_e32 v16, s40
	v_mov_b32_e32 v17, s43
	v_mov_b32_e32 v18, s42
	v_mov_b32_e32 v19, s45
	v_mov_b32_e32 v20, s44
	v_mov_b32_e32 v21, s47
	v_mov_b32_e32 v22, s46
	v_mov_b32_e32 v23, s49
	v_mov_b32_e32 v24, s48
	v_mov_b32_e32 v25, s55
	v_mov_b32_e32 v26, s54
	v_cndmask_b32_e32 v14, v13, v14, vcc
	v_cndmask_b32_e32 v12, v11, v12, vcc
	v_cndmask_b32_e32 v16, v15, v16, vcc
	v_cndmask_b32_e32 v18, v17, v18, vcc
	v_cndmask_b32_e32 v20, v19, v20, vcc
	v_cndmask_b32_e32 v22, v21, v22, vcc
	v_cndmask_b32_e32 v24, v23, v24, vcc
	v_cndmask_b32_e32 v26, v25, v26, vcc
	v_ashrrev_i32_e32 v15, 31, v14
	v_ashrrev_i32_e32 v13, 31, v12
	v_ashrrev_i32_e32 v17, 31, v16
	v_ashrrev_i32_e32 v19, 31, v18
	v_ashrrev_i32_e32 v21, 31, v20
	v_ashrrev_i32_e32 v23, 31, v22
	v_ashrrev_i32_e32 v25, 31, v24
	v_ashrrev_i32_e32 v27, 31, v26
	v_lshlrev_b64 v[14:15], 14, v[14:15]
	v_lshlrev_b64 v[12:13], 14, v[12:13]
	v_lshlrev_b64 v[16:17], 14, v[16:17]
	v_lshlrev_b64 v[18:19], 14, v[18:19]
	v_lshlrev_b64 v[20:21], 14, v[20:21]
	v_lshlrev_b64 v[22:23], 14, v[22:23]
	v_lshlrev_b64 v[24:25], 14, v[24:25]
	v_lshlrev_b64 v[26:27], 14, v[26:27]
	v_lshl_add_u64 v[14:15], v[2:3], 0, v[14:15]
	v_lshl_add_u64 v[12:13], v[2:3], 0, v[12:13]
	v_lshl_add_u64 v[16:17], v[2:3], 0, v[16:17]
	v_lshl_add_u64 v[18:19], v[2:3], 0, v[18:19]
	v_lshl_add_u64 v[20:21], v[2:3], 0, v[20:21]
	v_lshl_add_u64 v[22:23], v[2:3], 0, v[22:23]
	v_lshl_add_u64 v[24:25], v[2:3], 0, v[24:25]
	v_lshl_add_u64 v[26:27], v[2:3], 0, v[26:27]
	global_load_ushort v11, v[14:15], off
	global_load_ushort v28, v[16:17], off
	global_load_ushort v29, v[18:19], off
	global_load_ushort v30, v[20:21], off
	global_load_ushort v31, v[22:23], off
	global_load_ushort v32, v[24:25], off
	global_load_ushort v33, v[26:27], off
	global_load_ushort v34, v[12:13], off
	v_cvt_pk_bf16_f32 v35, v0, s0
	s_add_i32 s0, s0, -8
	global_store_short v[14:15], v35, off
	s_add_i32 s1, s1, 8
	s_cmpk_lg_i32 s1, 0x47
	s_waitcnt vmcnt(8)
	v_lshlrev_b32_e32 v11, 16, v11
	s_waitcnt vmcnt(7)
	v_lshlrev_b32_e32 v14, 16, v28
	v_fmac_f32_e32 v11, v10, v0
	s_waitcnt vmcnt(6)
	v_lshlrev_b32_e32 v15, 16, v29
	v_cvt_pk_bf16_f32 v0, v11, s0
	v_fmac_f32_e32 v14, v10, v11
	s_waitcnt vmcnt(5)
	v_lshlrev_b32_e32 v28, 16, v30
	global_store_short v[16:17], v0, off
	v_cvt_pk_bf16_f32 v0, v14, s0
	v_fmac_f32_e32 v15, v10, v14
	s_waitcnt vmcnt(5)
	v_lshlrev_b32_e32 v29, 16, v31
	global_store_short v[18:19], v0, off
	v_cvt_pk_bf16_f32 v0, v15, s0
	v_fmac_f32_e32 v28, v10, v15
	s_waitcnt vmcnt(5)
	v_lshlrev_b32_e32 v30, 16, v32
	global_store_short v[20:21], v0, off
	v_cvt_pk_bf16_f32 v0, v28, s0
	v_fmac_f32_e32 v29, v10, v28
	s_waitcnt vmcnt(5)
	v_lshlrev_b32_e32 v31, 16, v33
	global_store_short v[22:23], v0, off
	v_cvt_pk_bf16_f32 v0, v29, s0
	v_fmac_f32_e32 v30, v10, v29
	s_waitcnt vmcnt(5)
	v_lshlrev_b32_e32 v32, 16, v34
	global_store_short v[24:25], v0, off
	v_cvt_pk_bf16_f32 v0, v30, s0
	v_fmac_f32_e32 v31, v10, v30
	global_store_short v[26:27], v0, off
	v_cvt_pk_bf16_f32 v0, v31, s0
	v_fmac_f32_e32 v32, v10, v31
	global_store_short v[12:13], v0, off
	v_mov_b32_e32 v0, v32
	s_cbranch_scc1 .LBB0_808
	s_branch .Lmy_rs_join
.Lmy_rs_new:
	s_and_b64 s[38:39], vcc, exec
	s_cmp_lg_u64 s[38:39], 0
	s_mov_b32 s44, 0xffffc000
	s_cselect_b32 s40, 0x4000, s44
	s_cselect_b32 s41, 0, -1
	s_cselect_b32 s42, 0, 0xfc000
	s_mov_b32 s43, 0
	v_lshl_add_u64 v[12:13], v[2:3], 0, s[42:43]
	v_mov_b32_e32 v14, v12
	v_mov_b32_e32 v15, v13
	v_mov_b32_e32 v20, 0
	v_mov_b32_e32 v21, 0
	global_load_dword v40, v[12:13], off
	v_lshl_add_u64 v[12:13], v[12:13], 0, s[40:41]
	global_load_dword v41, v[12:13], off
	v_lshl_add_u64 v[12:13], v[12:13], 0, s[40:41]
	global_load_dword v42, v[12:13], off
	v_lshl_add_u64 v[12:13], v[12:13], 0, s[40:41]
	global_load_dword v43, v[12:13], off
	v_lshl_add_u64 v[12:13], v[12:13], 0, s[40:41]
	global_load_dword v44, v[12:13], off
	v_lshl_add_u64 v[12:13], v[12:13], 0, s[40:41]
	global_load_dword v45, v[12:13], off
	v_lshl_add_u64 v[12:13], v[12:13], 0, s[40:41]
	global_load_dword v46, v[12:13], off
	v_lshl_add_u64 v[12:13], v[12:13], 0, s[40:41]
	global_load_dword v47, v[12:13], off
	v_lshl_add_u64 v[12:13], v[12:13], 0, s[40:41]
	global_load_dword v48, v[12:13], off
	v_lshl_add_u64 v[12:13], v[12:13], 0, s[40:41]
	global_load_dword v49, v[12:13], off
	v_lshl_add_u64 v[12:13], v[12:13], 0, s[40:41]
	global_load_dword v50, v[12:13], off
	v_lshl_add_u64 v[12:13], v[12:13], 0, s[40:41]
	global_load_dword v51, v[12:13], off
	v_lshl_add_u64 v[12:13], v[12:13], 0, s[40:41]
	global_load_dword v52, v[12:13], off
	v_lshl_add_u64 v[12:13], v[12:13], 0, s[40:41]
	global_load_dword v53, v[12:13], off
	v_lshl_add_u64 v[12:13], v[12:13], 0, s[40:41]
	global_load_dword v54, v[12:13], off
	v_lshl_add_u64 v[12:13], v[12:13], 0, s[40:41]
	global_load_dword v55, v[12:13], off
	v_lshl_add_u64 v[12:13], v[12:13], 0, s[40:41]
	global_load_dword v56, v[12:13], off
	v_lshl_add_u64 v[12:13], v[12:13], 0, s[40:41]
	global_load_dword v57, v[12:13], off
	v_lshl_add_u64 v[12:13], v[12:13], 0, s[40:41]
	global_load_dword v58, v[12:13], off
	v_lshl_add_u64 v[12:13], v[12:13], 0, s[40:41]
	global_load_dword v59, v[12:13], off
	v_lshl_add_u64 v[12:13], v[12:13], 0, s[40:41]
	global_load_dword v60, v[12:13], off
	v_lshl_add_u64 v[12:13], v[12:13], 0, s[40:41]
	global_load_dword v61, v[12:13], off
	v_lshl_add_u64 v[12:13], v[12:13], 0, s[40:41]
	global_load_dword v62, v[12:13], off
	v_lshl_add_u64 v[12:13], v[12:13], 0, s[40:41]
	global_load_dword v63, v[12:13], off
	v_lshl_add_u64 v[12:13], v[12:13], 0, s[40:41]
	global_load_dword v64, v[12:13], off
	v_lshl_add_u64 v[12:13], v[12:13], 0, s[40:41]
	global_load_dword v65, v[12:13], off
	v_lshl_add_u64 v[12:13], v[12:13], 0, s[40:41]
	global_load_dword v66, v[12:13], off
	v_lshl_add_u64 v[12:13], v[12:13], 0, s[40:41]
	global_load_dword v67, v[12:13], off
	v_lshl_add_u64 v[12:13], v[12:13], 0, s[40:41]
	global_load_dword v68, v[12:13], off
	v_lshl_add_u64 v[12:13], v[12:13], 0, s[40:41]
	global_load_dword v69, v[12:13], off
	v_lshl_add_u64 v[12:13], v[12:13], 0, s[40:41]
	global_load_dword v70, v[12:13], off
	v_lshl_add_u64 v[12:13], v[12:13], 0, s[40:41]
	global_load_dword v71, v[12:13], off
	v_lshl_add_u64 v[12:13], v[12:13], 0, s[40:41]
	global_load_dword v72, v[12:13], off
	v_lshl_add_u64 v[12:13], v[12:13], 0, s[40:41]
	v_cvt_pk_bf16_f32 v16, v20, v21
	s_waitcnt vmcnt(32)
	global_store_dword v[14:15], v16, off
	v_lshl_add_u64 v[14:15], v[14:15], 0, s[40:41]
	v_lshlrev_b32_e32 v24, 16, v40
	v_and_b32_e32 v25, 0xffff0000, v40
	v_fmac_f32_e32 v24, v10, v20
	v_fmac_f32_e32 v25, v10, v21
	global_load_dword v73, v[12:13], off
	v_lshl_add_u64 v[12:13], v[12:13], 0, s[40:41]
	v_cvt_pk_bf16_f32 v16, v24, v25
	s_waitcnt vmcnt(33)
	global_store_dword v[14:15], v16, off
	v_lshl_add_u64 v[14:15], v[14:15], 0, s[40:41]
	v_lshlrev_b32_e32 v20, 16, v41
	v_and_b32_e32 v21, 0xffff0000, v41
	v_fmac_f32_e32 v20, v10, v24
	v_fmac_f32_e32 v21, v10, v25
	global_load_dword v74, v[12:13], off
	v_lshl_add_u64 v[12:13], v[12:13], 0, s[40:41]
	v_cvt_pk_bf16_f32 v16, v20, v21
	s_waitcnt vmcnt(34)
	global_store_dword v[14:15], v16, off
	v_lshl_add_u64 v[14:15], v[14:15], 0, s[40:41]
	v_lshlrev_b32_e32 v24, 16, v42
	v_and_b32_e32 v25, 0xffff0000, v42
	v_fmac_f32_e32 v24, v10, v20
	v_fmac_f32_e32 v25, v10, v21
	global_load_dword v75, v[12:13], off
	v_lshl_add_u64 v[12:13], v[12:13], 0, s[40:41]
	v_cvt_pk_bf16_f32 v16, v24, v25
	s_waitcnt vmcnt(35)
	global_store_dword v[14:15], v16, off
	v_lshl_add_u64 v[14:15], v[14:15], 0, s[40:41]
	v_lshlrev_b32_e32 v20, 16, v43
	v_and_b32_e32 v21, 0xffff0000, v43
	v_fmac_f32_e32 v20, v10, v24
	v_fmac_f32_e32 v21, v10, v25
	global_load_dword v76, v[12:13], off
	v_lshl_add_u64 v[12:13], v[12:13], 0, s[40:41]
	v_cvt_pk_bf16_f32 v16, v20, v21
	s_waitcnt vmcnt(36)
	global_store_dword v[14:15], v16, off
	v_lshl_add_u64 v[14:15], v[14:15], 0, s[40:41]
	v_lshlrev_b32_e32 v24, 16, v44
	v_and_b32_e32 v25, 0xffff0000, v44
	v_fmac_f32_e32 v24, v10, v20
	v_fmac_f32_e32 v25, v10, v21
	global_load_dword v77, v[12:13], off
	v_lshl_add_u64 v[12:13], v[12:13], 0, s[40:41]
	v_cvt_pk_bf16_f32 v16, v24, v25
	s_waitcnt vmcnt(37)
	global_store_dword v[14:15], v16, off
	v_lshl_add_u64 v[14:15], v[14:15], 0, s[40:41]
	v_lshlrev_b32_e32 v20, 16, v45
	v_and_b32_e32 v21, 0xffff0000, v45
	v_fmac_f32_e32 v20, v10, v24
	v_fmac_f32_e32 v21, v10, v25
	global_load_dword v78, v[12:13], off
	v_lshl_add_u64 v[12:13], v[12:13], 0, s[40:41]
	v_cvt_pk_bf16_f32 v16, v20, v21
	s_waitcnt vmcnt(38)
	global_store_dword v[14:15], v16, off
	v_lshl_add_u64 v[14:15], v[14:15], 0, s[40:41]
	v_lshlrev_b32_e32 v24, 16, v46
	v_and_b32_e32 v25, 0xffff0000, v46
	v_fmac_f32_e32 v24, v10, v20
	v_fmac_f32_e32 v25, v10, v21
	global_load_dword v79, v[12:13], off
	v_lshl_add_u64 v[12:13], v[12:13], 0, s[40:41]
	v_cvt_pk_bf16_f32 v16, v24, v25
	s_waitcnt vmcnt(39)
	global_store_dword v[14:15], v16, off
	v_lshl_add_u64 v[14:15], v[14:15], 0, s[40:41]
	v_lshlrev_b32_e32 v20, 16, v47
	v_and_b32_e32 v21, 0xffff0000, v47
	v_fmac_f32_e32 v20, v10, v24
	v_fmac_f32_e32 v21, v10, v25
	global_load_dword v80, v[12:13], off
	v_lshl_add_u64 v[12:13], v[12:13], 0, s[40:41]
	v_cvt_pk_bf16_f32 v16, v20, v21
	s_waitcnt vmcnt(40)
	global_store_dword v[14:15], v16, off
	v_lshl_add_u64 v[14:15], v[14:15], 0, s[40:41]
	v_lshlrev_b32_e32 v24, 16, v48
	v_and_b32_e32 v25, 0xffff0000, v48
	v_fmac_f32_e32 v24, v10, v20
	v_fmac_f32_e32 v25, v10, v21
	global_load_dword v81, v[12:13], off
	v_lshl_add_u64 v[12:13], v[12:13], 0, s[40:41]
	v_cvt_pk_bf16_f32 v16, v24, v25
	s_waitcnt vmcnt(41)
	global_store_dword v[14:15], v16, off
	v_lshl_add_u64 v[14:15], v[14:15], 0, s[40:41]
	v_lshlrev_b32_e32 v20, 16, v49
	v_and_b32_e32 v21, 0xffff0000, v49
	v_fmac_f32_e32 v20, v10, v24
	v_fmac_f32_e32 v21, v10, v25
	global_load_dword v82, v[12:13], off
	v_lshl_add_u64 v[12:13], v[12:13], 0, s[40:41]
	v_cvt_pk_bf16_f32 v16, v20, v21
	s_waitcnt vmcnt(42)
	global_store_dword v[14:15], v16, off
	v_lshl_add_u64 v[14:15], v[14:15], 0, s[40:41]
	v_lshlrev_b32_e32 v24, 16, v50
	v_and_b32_e32 v25, 0xffff0000, v50
	v_fmac_f32_e32 v24, v10, v20
	v_fmac_f32_e32 v25, v10, v21
	global_load_dword v83, v[12:13], off
	v_lshl_add_u64 v[12:13], v[12:13], 0, s[40:41]
	v_cvt_pk_bf16_f32 v16, v24, v25
	s_waitcnt vmcnt(43)
	global_store_dword v[14:15], v16, off
	v_lshl_add_u64 v[14:15], v[14:15], 0, s[40:41]
	v_lshlrev_b32_e32 v20, 16, v51
	v_and_b32_e32 v21, 0xffff0000, v51
	v_fmac_f32_e32 v20, v10, v24
	v_fmac_f32_e32 v21, v10, v25
	global_load_dword v84, v[12:13], off
	v_lshl_add_u64 v[12:13], v[12:13], 0, s[40:41]
	v_cvt_pk_bf16_f32 v16, v20, v21
	s_waitcnt vmcnt(44)
	global_store_dword v[14:15], v16, off
	v_lshl_add_u64 v[14:15], v[14:15], 0, s[40:41]
	v_lshlrev_b32_e32 v24, 16, v52
	v_and_b32_e32 v25, 0xffff0000, v52
	v_fmac_f32_e32 v24, v10, v20
	v_fmac_f32_e32 v25, v10, v21
	global_load_dword v85, v[12:13], off
	v_lshl_add_u64 v[12:13], v[12:13], 0, s[40:41]
	v_cvt_pk_bf16_f32 v16, v24, v25
	s_waitcnt vmcnt(45)
	global_store_dword v[14:15], v16, off
	v_lshl_add_u64 v[14:15], v[14:15], 0, s[40:41]
	v_lshlrev_b32_e32 v20, 16, v53
	v_and_b32_e32 v21, 0xffff0000, v53
	v_fmac_f32_e32 v20, v10, v24
	v_fmac_f32_e32 v21, v10, v25
	global_load_dword v86, v[12:13], off
	v_lshl_add_u64 v[12:13], v[12:13], 0, s[40:41]
	v_cvt_pk_bf16_f32 v16, v20, v21
	s_waitcnt vmcnt(46)
	global_store_dword v[14:15], v16, off
	v_lshl_add_u64 v[14:15], v[14:15], 0, s[40:41]
	v_lshlrev_b32_e32 v24, 16, v54
	v_and_b32_e32 v25, 0xffff0000, v54
	v_fmac_f32_e32 v24, v10, v20
	v_fmac_f32_e32 v25, v10, v21
	global_load_dword v87, v[12:13], off
	v_lshl_add_u64 v[12:13], v[12:13], 0, s[40:41]
	v_cvt_pk_bf16_f32 v16, v24, v25
	s_waitcnt vmcnt(47)
	global_store_dword v[14:15], v16, off
	v_lshl_add_u64 v[14:15], v[14:15], 0, s[40:41]
	v_lshlrev_b32_e32 v20, 16, v55
	v_and_b32_e32 v21, 0xffff0000, v55
	v_fmac_f32_e32 v20, v10, v24
	v_fmac_f32_e32 v21, v10, v25
	global_load_dword v88, v[12:13], off
	v_lshl_add_u64 v[12:13], v[12:13], 0, s[40:41]
	v_cvt_pk_bf16_f32 v16, v20, v21
	s_waitcnt vmcnt(48)
	global_store_dword v[14:15], v16, off
	v_lshl_add_u64 v[14:15], v[14:15], 0, s[40:41]
	v_lshlrev_b32_e32 v24, 16, v56
	v_and_b32_e32 v25, 0xffff0000, v56
	v_fmac_f32_e32 v24, v10, v20
	v_fmac_f32_e32 v25, v10, v21
	global_load_dword v89, v[12:13], off
	v_lshl_add_u64 v[12:13], v[12:13], 0, s[40:41]
	v_cvt_pk_bf16_f32 v16, v24, v25
	s_waitcnt vmcnt(49)
	global_store_dword v[14:15], v16, off
	v_lshl_add_u64 v[14:15], v[14:15], 0, s[40:41]
	v_lshlrev_b32_e32 v20, 16, v57
	v_and_b32_e32 v21, 0xffff0000, v57
	v_fmac_f32_e32 v20, v10, v24
	v_fmac_f32_e32 v21, v10, v25
	global_load_dword v90, v[12:13], off
	v_lshl_add_u64 v[12:13], v[12:13], 0, s[40:41]
	v_cvt_pk_bf16_f32 v16, v20, v21
	s_waitcnt vmcnt(50)
	global_store_dword v[14:15], v16, off
	v_lshl_add_u64 v[14:15], v[14:15], 0, s[40:41]
	v_lshlrev_b32_e32 v24, 16, v58
	v_and_b32_e32 v25, 0xffff0000, v58
	v_fmac_f32_e32 v24, v10, v20
	v_fmac_f32_e32 v25, v10, v21
	global_load_dword v91, v[12:13], off
	v_lshl_add_u64 v[12:13], v[12:13], 0, s[40:41]
	v_cvt_pk_bf16_f32 v16, v24, v25
	s_waitcnt vmcnt(51)
	global_store_dword v[14:15], v16, off
	v_lshl_add_u64 v[14:15], v[14:15], 0, s[40:41]
	v_lshlrev_b32_e32 v20, 16, v59
	v_and_b32_e32 v21, 0xffff0000, v59
	v_fmac_f32_e32 v20, v10, v24
	v_fmac_f32_e32 v21, v10, v25
	global_load_dword v92, v[12:13], off
	v_lshl_add_u64 v[12:13], v[12:13], 0, s[40:41]
	v_cvt_pk_bf16_f32 v16, v20, v21
	s_waitcnt vmcnt(52)
	global_store_dword v[14:15], v16, off
	v_lshl_add_u64 v[14:15], v[14:15], 0, s[40:41]
	v_lshlrev_b32_e32 v24, 16, v60
	v_and_b32_e32 v25, 0xffff0000, v60
	v_fmac_f32_e32 v24, v10, v20
	v_fmac_f32_e32 v25, v10, v21
	global_load_dword v93, v[12:13], off
	v_lshl_add_u64 v[12:13], v[12:13], 0, s[40:41]
	v_cvt_pk_bf16_f32 v16, v24, v25
	s_waitcnt vmcnt(53)
	global_store_dword v[14:15], v16, off
	v_lshl_add_u64 v[14:15], v[14:15], 0, s[40:41]
	v_lshlrev_b32_e32 v20, 16, v61
	v_and_b32_e32 v21, 0xffff0000, v61
	v_fmac_f32_e32 v20, v10, v24
	v_fmac_f32_e32 v21, v10, v25
	global_load_dword v94, v[12:13], off
	v_lshl_add_u64 v[12:13], v[12:13], 0, s[40:41]
	v_cvt_pk_bf16_f32 v16, v20, v21
	s_waitcnt vmcnt(54)
	global_store_dword v[14:15], v16, off
	v_lshl_add_u64 v[14:15], v[14:15], 0, s[40:41]
	v_lshlrev_b32_e32 v24, 16, v62
	v_and_b32_e32 v25, 0xffff0000, v62
	v_fmac_f32_e32 v24, v10, v20
	v_fmac_f32_e32 v25, v10, v21
	global_load_dword v95, v[12:13], off
	v_lshl_add_u64 v[12:13], v[12:13], 0, s[40:41]
	v_cvt_pk_bf16_f32 v16, v24, v25
	s_waitcnt vmcnt(55)
	global_store_dword v[14:15], v16, off
	v_lshl_add_u64 v[14:15], v[14:15], 0, s[40:41]
	v_lshlrev_b32_e32 v20, 16, v63
	v_and_b32_e32 v21, 0xffff0000, v63
	v_fmac_f32_e32 v20, v10, v24
	v_fmac_f32_e32 v21, v10, v25
	global_load_dword v96, v[12:13], off
	v_lshl_add_u64 v[12:13], v[12:13], 0, s[40:41]
	v_cvt_pk_bf16_f32 v16, v20, v21
	s_waitcnt vmcnt(56)
	global_store_dword v[14:15], v16, off
	v_lshl_add_u64 v[14:15], v[14:15], 0, s[40:41]
	v_lshlrev_b32_e32 v24, 16, v64
	v_and_b32_e32 v25, 0xffff0000, v64
	v_fmac_f32_e32 v24, v10, v20
	v_fmac_f32_e32 v25, v10, v21
	global_load_dword v97, v[12:13], off
	v_lshl_add_u64 v[12:13], v[12:13], 0, s[40:41]
	v_cvt_pk_bf16_f32 v16, v24, v25
	s_waitcnt vmcnt(57)
	global_store_dword v[14:15], v16, off
	v_lshl_add_u64 v[14:15], v[14:15], 0, s[40:41]
	v_lshlrev_b32_e32 v20, 16, v65
	v_and_b32_e32 v21, 0xffff0000, v65
	v_fmac_f32_e32 v20, v10, v24
	v_fmac_f32_e32 v21, v10, v25
	global_load_dword v98, v[12:13], off
	v_lshl_add_u64 v[12:13], v[12:13], 0, s[40:41]
	v_cvt_pk_bf16_f32 v16, v20, v21
	s_waitcnt vmcnt(58)
	global_store_dword v[14:15], v16, off
	v_lshl_add_u64 v[14:15], v[14:15], 0, s[40:41]
	v_lshlrev_b32_e32 v24, 16, v66
	v_and_b32_e32 v25, 0xffff0000, v66
	v_fmac_f32_e32 v24, v10, v20
	v_fmac_f32_e32 v25, v10, v21
	global_load_dword v99, v[12:13], off
	v_lshl_add_u64 v[12:13], v[12:13], 0, s[40:41]
	v_cvt_pk_bf16_f32 v16, v24, v25
	s_waitcnt vmcnt(59)
	global_store_dword v[14:15], v16, off
	v_lshl_add_u64 v[14:15], v[14:15], 0, s[40:41]
	v_lshlrev_b32_e32 v20, 16, v67
	v_and_b32_e32 v21, 0xffff0000, v67
	v_fmac_f32_e32 v20, v10, v24
	v_fmac_f32_e32 v21, v10, v25
	global_load_dword v100, v[12:13], off
	v_lshl_add_u64 v[12:13], v[12:13], 0, s[40:41]
	v_cvt_pk_bf16_f32 v16, v20, v21
	s_waitcnt vmcnt(60)
	global_store_dword v[14:15], v16, off
	v_lshl_add_u64 v[14:15], v[14:15], 0, s[40:41]
	v_lshlrev_b32_e32 v24, 16, v68
	v_and_b32_e32 v25, 0xffff0000, v68
	v_fmac_f32_e32 v24, v10, v20
	v_fmac_f32_e32 v25, v10, v21
	global_load_dword v101, v[12:13], off
	v_lshl_add_u64 v[12:13], v[12:13], 0, s[40:41]
	v_cvt_pk_bf16_f32 v16, v24, v25
	s_waitcnt vmcnt(61)
	global_store_dword v[14:15], v16, off
	v_lshl_add_u64 v[14:15], v[14:15], 0, s[40:41]
	v_lshlrev_b32_e32 v20, 16, v69
	v_and_b32_e32 v21, 0xffff0000, v69
	v_fmac_f32_e32 v20, v10, v24
	v_fmac_f32_e32 v21, v10, v25
	global_load_dword v102, v[12:13], off
	v_lshl_add_u64 v[12:13], v[12:13], 0, s[40:41]
	v_cvt_pk_bf16_f32 v16, v20, v21
	s_waitcnt vmcnt(62)
	global_store_dword v[14:15], v16, off
	v_lshl_add_u64 v[14:15], v[14:15], 0, s[40:41]
	v_lshlrev_b32_e32 v24, 16, v70
	v_and_b32_e32 v25, 0xffff0000, v70
	v_fmac_f32_e32 v24, v10, v20
	v_fmac_f32_e32 v25, v10, v21
	global_load_dword v103, v[12:13], off
	v_lshl_add_u64 v[12:13], v[12:13], 0, s[40:41]
	v_cvt_pk_bf16_f32 v16, v24, v25
	s_waitcnt vmcnt(63)
	global_store_dword v[14:15], v16, off
	v_lshl_add_u64 v[14:15], v[14:15], 0, s[40:41]
	v_lshlrev_b32_e32 v20, 16, v71
	v_and_b32_e32 v21, 0xffff0000, v71
	v_fmac_f32_e32 v20, v10, v24
	v_fmac_f32_e32 v21, v10, v25
	v_cvt_pk_bf16_f32 v16, v20, v21
	s_waitcnt vmcnt(63)
	global_store_dword v[14:15], v16, off
	v_lshl_add_u64 v[14:15], v[14:15], 0, s[40:41]
	v_lshlrev_b32_e32 v24, 16, v72
	v_and_b32_e32 v25, 0xffff0000, v72
	v_fmac_f32_e32 v24, v10, v20
	v_fmac_f32_e32 v25, v10, v21
	v_cvt_pk_bf16_f32 v16, v24, v25
	s_waitcnt vmcnt(62)
	global_store_dword v[14:15], v16, off
	v_lshl_add_u64 v[14:15], v[14:15], 0, s[40:41]
	v_lshlrev_b32_e32 v20, 16, v73
	v_and_b32_e32 v21, 0xffff0000, v73
	v_fmac_f32_e32 v20, v10, v24
	v_fmac_f32_e32 v21, v10, v25
	v_cvt_pk_bf16_f32 v16, v20, v21
	s_waitcnt vmcnt(61)
	global_store_dword v[14:15], v16, off
	v_lshl_add_u64 v[14:15], v[14:15], 0, s[40:41]
	v_lshlrev_b32_e32 v24, 16, v74
	v_and_b32_e32 v25, 0xffff0000, v74
	v_fmac_f32_e32 v24, v10, v20
	v_fmac_f32_e32 v25, v10, v21
	v_cvt_pk_bf16_f32 v16, v24, v25
	s_waitcnt vmcnt(60)
	global_store_dword v[14:15], v16, off
	v_lshl_add_u64 v[14:15], v[14:15], 0, s[40:41]
	v_lshlrev_b32_e32 v20, 16, v75
	v_and_b32_e32 v21, 0xffff0000, v75
	v_fmac_f32_e32 v20, v10, v24
	v_fmac_f32_e32 v21, v10, v25
	v_cvt_pk_bf16_f32 v16, v20, v21
	s_waitcnt vmcnt(59)
	global_store_dword v[14:15], v16, off
	v_lshl_add_u64 v[14:15], v[14:15], 0, s[40:41]
	v_lshlrev_b32_e32 v24, 16, v76
	v_and_b32_e32 v25, 0xffff0000, v76
	v_fmac_f32_e32 v24, v10, v20
	v_fmac_f32_e32 v25, v10, v21
	v_cvt_pk_bf16_f32 v16, v24, v25
	s_waitcnt vmcnt(58)
	global_store_dword v[14:15], v16, off
	v_lshl_add_u64 v[14:15], v[14:15], 0, s[40:41]
	v_lshlrev_b32_e32 v20, 16, v77
	v_and_b32_e32 v21, 0xffff0000, v77
	v_fmac_f32_e32 v20, v10, v24
	v_fmac_f32_e32 v21, v10, v25
	v_cvt_pk_bf16_f32 v16, v20, v21
	s_waitcnt vmcnt(57)
	global_store_dword v[14:15], v16, off
	v_lshl_add_u64 v[14:15], v[14:15], 0, s[40:41]
	v_lshlrev_b32_e32 v24, 16, v78
	v_and_b32_e32 v25, 0xffff0000, v78
	v_fmac_f32_e32 v24, v10, v20
	v_fmac_f32_e32 v25, v10, v21
	v_cvt_pk_bf16_f32 v16, v24, v25
	s_waitcnt vmcnt(56)
	global_store_dword v[14:15], v16, off
	v_lshl_add_u64 v[14:15], v[14:15], 0, s[40:41]
	v_lshlrev_b32_e32 v20, 16, v79
	v_and_b32_e32 v21, 0xffff0000, v79
	v_fmac_f32_e32 v20, v10, v24
	v_fmac_f32_e32 v21, v10, v25
	v_cvt_pk_bf16_f32 v16, v20, v21
	s_waitcnt vmcnt(55)
	global_store_dword v[14:15], v16, off
	v_lshl_add_u64 v[14:15], v[14:15], 0, s[40:41]
	v_lshlrev_b32_e32 v24, 16, v80
	v_and_b32_e32 v25, 0xffff0000, v80
	v_fmac_f32_e32 v24, v10, v20
	v_fmac_f32_e32 v25, v10, v21
	v_cvt_pk_bf16_f32 v16, v24, v25
	s_waitcnt vmcnt(54)
	global_store_dword v[14:15], v16, off
	v_lshl_add_u64 v[14:15], v[14:15], 0, s[40:41]
	v_lshlrev_b32_e32 v20, 16, v81
	v_and_b32_e32 v21, 0xffff0000, v81
	v_fmac_f32_e32 v20, v10, v24
	v_fmac_f32_e32 v21, v10, v25
	v_cvt_pk_bf16_f32 v16, v20, v21
	s_waitcnt vmcnt(53)
	global_store_dword v[14:15], v16, off
	v_lshl_add_u64 v[14:15], v[14:15], 0, s[40:41]
	v_lshlrev_b32_e32 v24, 16, v82
	v_and_b32_e32 v25, 0xffff0000, v82
	v_fmac_f32_e32 v24, v10, v20
	v_fmac_f32_e32 v25, v10, v21
	v_cvt_pk_bf16_f32 v16, v24, v25
	s_waitcnt vmcnt(52)
	global_store_dword v[14:15], v16, off
	v_lshl_add_u64 v[14:15], v[14:15], 0, s[40:41]
	v_lshlrev_b32_e32 v20, 16, v83
	v_and_b32_e32 v21, 0xffff0000, v83
	v_fmac_f32_e32 v20, v10, v24
	v_fmac_f32_e32 v21, v10, v25
	v_cvt_pk_bf16_f32 v16, v20, v21
	s_waitcnt vmcnt(51)
	global_store_dword v[14:15], v16, off
	v_lshl_add_u64 v[14:15], v[14:15], 0, s[40:41]
	v_lshlrev_b32_e32 v24, 16, v84
	v_and_b32_e32 v25, 0xffff0000, v84
	v_fmac_f32_e32 v24, v10, v20
	v_fmac_f32_e32 v25, v10, v21
	v_cvt_pk_bf16_f32 v16, v24, v25
	s_waitcnt vmcnt(50)
	global_store_dword v[14:15], v16, off
	v_lshl_add_u64 v[14:15], v[14:15], 0, s[40:41]
	v_lshlrev_b32_e32 v20, 16, v85
	v_and_b32_e32 v21, 0xffff0000, v85
	v_fmac_f32_e32 v20, v10, v24
	v_fmac_f32_e32 v21, v10, v25
	v_cvt_pk_bf16_f32 v16, v20, v21
	s_waitcnt vmcnt(49)
	global_store_dword v[14:15], v16, off
	v_lshl_add_u64 v[14:15], v[14:15], 0, s[40:41]
	v_lshlrev_b32_e32 v24, 16, v86
	v_and_b32_e32 v25, 0xffff0000, v86
	v_fmac_f32_e32 v24, v10, v20
	v_fmac_f32_e32 v25, v10, v21
	v_cvt_pk_bf16_f32 v16, v24, v25
	s_waitcnt vmcnt(48)
	global_store_dword v[14:15], v16, off
	v_lshl_add_u64 v[14:15], v[14:15], 0, s[40:41]
	v_lshlrev_b32_e32 v20, 16, v87
	v_and_b32_e32 v21, 0xffff0000, v87
	v_fmac_f32_e32 v20, v10, v24
	v_fmac_f32_e32 v21, v10, v25
	v_cvt_pk_bf16_f32 v16, v20, v21
	s_waitcnt vmcnt(47)
	global_store_dword v[14:15], v16, off
	v_lshl_add_u64 v[14:15], v[14:15], 0, s[40:41]
	v_lshlrev_b32_e32 v24, 16, v88
	v_and_b32_e32 v25, 0xffff0000, v88
	v_fmac_f32_e32 v24, v10, v20
	v_fmac_f32_e32 v25, v10, v21
	v_cvt_pk_bf16_f32 v16, v24, v25
	s_waitcnt vmcnt(46)
	global_store_dword v[14:15], v16, off
	v_lshl_add_u64 v[14:15], v[14:15], 0, s[40:41]
	v_lshlrev_b32_e32 v20, 16, v89
	v_and_b32_e32 v21, 0xffff0000, v89
	v_fmac_f32_e32 v20, v10, v24
	v_fmac_f32_e32 v21, v10, v25
	v_cvt_pk_bf16_f32 v16, v20, v21
	s_waitcnt vmcnt(45)
	global_store_dword v[14:15], v16, off
	v_lshl_add_u64 v[14:15], v[14:15], 0, s[40:41]
	v_lshlrev_b32_e32 v24, 16, v90
	v_and_b32_e32 v25, 0xffff0000, v90
	v_fmac_f32_e32 v24, v10, v20
	v_fmac_f32_e32 v25, v10, v21
	v_cvt_pk_bf16_f32 v16, v24, v25
	s_waitcnt vmcnt(44)
	global_store_dword v[14:15], v16, off
	v_lshl_add_u64 v[14:15], v[14:15], 0, s[40:41]
	v_lshlrev_b32_e32 v20, 16, v91
	v_and_b32_e32 v21, 0xffff0000, v91
	v_fmac_f32_e32 v20, v10, v24
	v_fmac_f32_e32 v21, v10, v25
	v_cvt_pk_bf16_f32 v16, v20, v21
	s_waitcnt vmcnt(43)
	global_store_dword v[14:15], v16, off
	v_lshl_add_u64 v[14:15], v[14:15], 0, s[40:41]
	v_lshlrev_b32_e32 v24, 16, v92
	v_and_b32_e32 v25, 0xffff0000, v92
	v_fmac_f32_e32 v24, v10, v20
	v_fmac_f32_e32 v25, v10, v21
	v_cvt_pk_bf16_f32 v16, v24, v25
	s_waitcnt vmcnt(42)
	global_store_dword v[14:15], v16, off
	v_lshl_add_u64 v[14:15], v[14:15], 0, s[40:41]
	v_lshlrev_b32_e32 v20, 16, v93
	v_and_b32_e32 v21, 0xffff0000, v93
	v_fmac_f32_e32 v20, v10, v24
	v_fmac_f32_e32 v21, v10, v25
	v_cvt_pk_bf16_f32 v16, v20, v21
	s_waitcnt vmcnt(41)
	global_store_dword v[14:15], v16, off
	v_lshl_add_u64 v[14:15], v[14:15], 0, s[40:41]
	v_lshlrev_b32_e32 v24, 16, v94
	v_and_b32_e32 v25, 0xffff0000, v94
	v_fmac_f32_e32 v24, v10, v20
	v_fmac_f32_e32 v25, v10, v21
	v_cvt_pk_bf16_f32 v16, v24, v25
	s_waitcnt vmcnt(40)
	global_store_dword v[14:15], v16, off
	v_lshl_add_u64 v[14:15], v[14:15], 0, s[40:41]
	v_lshlrev_b32_e32 v20, 16, v95
	v_and_b32_e32 v21, 0xffff0000, v95
	v_fmac_f32_e32 v20, v10, v24
	v_fmac_f32_e32 v21, v10, v25
	v_cvt_pk_bf16_f32 v16, v20, v21
	s_waitcnt vmcnt(39)
	global_store_dword v[14:15], v16, off
	v_lshl_add_u64 v[14:15], v[14:15], 0, s[40:41]
	v_lshlrev_b32_e32 v24, 16, v96
	v_and_b32_e32 v25, 0xffff0000, v96
	v_fmac_f32_e32 v24, v10, v20
	v_fmac_f32_e32 v25, v10, v21
	v_cvt_pk_bf16_f32 v16, v24, v25
	s_waitcnt vmcnt(38)
	global_store_dword v[14:15], v16, off
	v_lshl_add_u64 v[14:15], v[14:15], 0, s[40:41]
	v_lshlrev_b32_e32 v20, 16, v97
	v_and_b32_e32 v21, 0xffff0000, v97
	v_fmac_f32_e32 v20, v10, v24
	v_fmac_f32_e32 v21, v10, v25
	v_cvt_pk_bf16_f32 v16, v20, v21
	s_waitcnt vmcnt(37)
	global_store_dword v[14:15], v16, off
	v_lshl_add_u64 v[14:15], v[14:15], 0, s[40:41]
	v_lshlrev_b32_e32 v24, 16, v98
	v_and_b32_e32 v25, 0xffff0000, v98
	v_fmac_f32_e32 v24, v10, v20
	v_fmac_f32_e32 v25, v10, v21
	v_cvt_pk_bf16_f32 v16, v24, v25
	s_waitcnt vmcnt(36)
	global_store_dword v[14:15], v16, off
	v_lshl_add_u64 v[14:15], v[14:15], 0, s[40:41]
	v_lshlrev_b32_e32 v20, 16, v99
	v_and_b32_e32 v21, 0xffff0000, v99
	v_fmac_f32_e32 v20, v10, v24
	v_fmac_f32_e32 v21, v10, v25
	v_cvt_pk_bf16_f32 v16, v20, v21
	s_waitcnt vmcnt(35)
	global_store_dword v[14:15], v16, off
	v_lshl_add_u64 v[14:15], v[14:15], 0, s[40:41]
	v_lshlrev_b32_e32 v24, 16, v100
	v_and_b32_e32 v25, 0xffff0000, v100
	v_fmac_f32_e32 v24, v10, v20
	v_fmac_f32_e32 v25, v10, v21
	v_cvt_pk_bf16_f32 v16, v24, v25
	s_waitcnt vmcnt(34)
	global_store_dword v[14:15], v16, off
	v_lshl_add_u64 v[14:15], v[14:15], 0, s[40:41]
	v_lshlrev_b32_e32 v20, 16, v101
	v_and_b32_e32 v21, 0xffff0000, v101
	v_fmac_f32_e32 v20, v10, v24
	v_fmac_f32_e32 v21, v10, v25
	v_cvt_pk_bf16_f32 v16, v20, v21
	s_waitcnt vmcnt(33)
	global_store_dword v[14:15], v16, off
	v_lshl_add_u64 v[14:15], v[14:15], 0, s[40:41]
	v_lshlrev_b32_e32 v24, 16, v102
	v_and_b32_e32 v25, 0xffff0000, v102
	v_fmac_f32_e32 v24, v10, v20
	v_fmac_f32_e32 v25, v10, v21
	v_cvt_pk_bf16_f32 v16, v24, v25
	s_waitcnt vmcnt(32)
	global_store_dword v[14:15], v16, off
	v_lshl_add_u64 v[14:15], v[14:15], 0, s[40:41]
	v_lshlrev_b32_e32 v20, 16, v103
	v_and_b32_e32 v21, 0xffff0000, v103
	v_fmac_f32_e32 v20, v10, v24
	v_fmac_f32_e32 v21, v10, v25
.Lmy_rs_join:
	v_add_u32_e32 v4, s71, v4
	v_cmp_lt_i32_e32 vcc, s35, v4
	s_or_b64 s[20:21], vcc, s[20:21]
	s_andn2_b64 exec, exec, s[20:21]
	s_cbranch_execnz .LBB0_807
